# in-proj gate-column tiles: k-loop loads hoisted to the start of the MFMA phase as well
# speedup vs baseline: 1.0096x; 1.0021x over previous
; DI int otid() { int t = threadIdx.x; asm volatile("" : "+v"(t)); return t; }
; template <class Epi>
; DI void gemm128(const bf16_t* __restrict__ A, int lda, const bf16_t* __restrict__ B, int ldb, int K, int m0, int n0,
;                 bf16_t* sA, bf16_t* sB, Epi epi) {
;   const int tid = otid(), lane = tid & 63, wave = tid >> 6;
;   const int wm = wave >> 1, wn = wave & 1;
;   const int lr = tid >> 3, lc = (tid & 7) * 8;
;   f32x16 acc[2][2];
; #pragma unroll
;   for (int i = 0; i < 2; ++i)
; #pragma unroll
;     for (int j = 0; j < 2; ++j)
; #pragma unroll
;       for (int r = 0; r < 16; ++r) acc[i][j][r] = 0.f;
;   u32x4 ra0, ra1, ra2, ra3, rb0, rb1, rb2, rb3;
;   const bf16_t* Ap = A + (size_t)(m0 + lr) * lda + lc;
;   const bf16_t* Bp = B + (size_t)(n0 + lr) * ldb + lc;
;   ra0 = *(const u32x4*)(Ap); ra1 = *(const u32x4*)(Ap + (size_t)32 * lda);
;   ra2 = *(const u32x4*)(Ap + (size_t)64 * lda); ra3 = *(const u32x4*)(Ap + (size_t)96 * lda);
;   rb0 = *(const u32x4*)(Bp); rb1 = *(const u32x4*)(Bp + (size_t)32 * ldb);
;   rb2 = *(const u32x4*)(Bp + (size_t)64 * ldb); rb3 = *(const u32x4*)(Bp + (size_t)96 * ldb);
;   const int nk = K >> 6;
; __global__ void __launch_bounds__(256, 2) hymba_mega(Params p) {
;     ...
;       } else {
;         const int mt = tile - 2048;
;         gemm128((const bf16_t*)p.out, 1024, (const bf16_t*)(ws + OFF_WINT), 1024, 1024, mt * 128, 4096, sA, sB,
;                 [&](int m, int n, float v) { if (n < 4112) G[(size_t)(n - 4096) * T_TOK + m] = v; });
.LBB0_221:
	s_ashr_i32 s7, s6, 31
	s_cmpk_gt_i32 s61, 0x7ff
	s_mov_b64 s[10:11], -1
	s_cbranch_scc0 .LBB0_227
	s_lshl_b32 s64, s61, 7
	v_mov_b32_e32 v72, v192
	s_add_i32 s64, s64, 0xfffc0000
	s_nop 0
	v_ashrrev_i32_e32 v0, 3, v72
	v_add_u32_e32 v2, s64, v0
	v_ashrrev_i32_e32 v3, 31, v2
	v_lshlrev_b64 v[2:3], 11, v[2:3]
	v_lshlrev_b32_e32 v1, 4, v72
	v_lshl_add_u64 v[2:3], s[84:85], 0, v[2:3]
	v_and_b32_e32 v176, 0x70, v1
	v_lshl_add_u64 v[2:3], v[2:3], 0, v[176:177]
	v_add_co_u32_e32 v8, vcc, s4, v2
	v_ashrrev_i32_e32 v1, 31, v0
	s_nop 0
	v_addc_co_u32_e32 v9, vcc, 0, v3, vcc
	global_load_dwordx4 v[200:203], v[2:3], off
	global_load_dwordx4 v[204:207], v[8:9], off
	v_add_co_u32_e32 v8, vcc, s5, v2
	v_lshlrev_b64 v[4:5], 11, v[0:1]
	s_nop 0
	v_addc_co_u32_e32 v9, vcc, 0, v3, vcc
	v_lshl_add_u64 v[6:7], s[8:9], 0, v[4:5]
	v_add_co_u32_e32 v2, vcc, s12, v2
	v_lshl_add_u64 v[6:7], v[6:7], 0, v[176:177]
	s_nop 0
	v_addc_co_u32_e32 v3, vcc, 0, v3, vcc
	global_load_dwordx4 v[208:211], v[8:9], off
	global_load_dwordx4 v[212:215], v[2:3], off
	v_add_co_u32_e32 v2, vcc, s13, v6
	v_mad_u64_u32 v[66:67], s[10:11], v0, s17, v[176:177]
	s_nop 0
	v_addc_co_u32_e32 v3, vcc, 0, v7, vcc
	v_add_co_u32_e32 v8, vcc, s14, v6
	v_lshl_add_u64 v[0:1], v[0:1], 0, s[6:7]
	s_nop 0
	v_addc_co_u32_e32 v9, vcc, 0, v7, vcc
	global_load_dwordx4 v[216:219], v[2:3], off
	global_load_dwordx4 v[220:223], v[8:9], off
	v_add_co_u32_e32 v2, vcc, s15, v6
	v_lshlrev_b64 v[0:1], 11, v[0:1]
	s_nop 0
	v_addc_co_u32_e32 v3, vcc, 0, v7, vcc
	v_add_co_u32_e32 v6, vcc, s16, v6
	v_or_b32_e32 v0, v0, v176
	s_nop 0
	v_addc_co_u32_e32 v7, vcc, 0, v7, vcc
	global_load_dwordx4 v[224:227], v[2:3], off
	global_load_dwordx4 v[232:235], v[6:7], off
	v_ashrrev_i32_e32 v2, 1, v72
	v_and_b32_e32 v67, 0xffffffc0, v2
	v_lshrrev_b32_e32 v2, 1, v72
	v_and_or_b32 v3, v72, 31, v67
	v_and_b32_e32 v2, 16, v2
	v_and_b32_e32 v73, 0x5f, v72
	v_mad_u64_u32 v[64:65], s[10:11], v3, s17, v[2:3]
	v_lshl_add_u64 v[68:69], s[84:85], 0, v[0:1]
	v_or_b32_e32 v4, v4, v176
	v_mov_b32_e32 v0, 0
	v_mad_u32_u24 v65, v73, s17, v2
	v_lshl_add_u64 v[70:71], s[86:87], 0, v[4:5]
	s_mov_b64 s[10:11], 0
	v_mov_b32_e32 v1, v0
	v_mov_b32_e32 v2, v0
	v_mov_b32_e32 v3, v0
	v_mov_b32_e32 v4, v0
	v_mov_b32_e32 v5, v0
	v_mov_b32_e32 v6, v0
	v_mov_b32_e32 v7, v0
	v_mov_b32_e32 v8, v0
	v_mov_b32_e32 v9, v0
	v_mov_b32_e32 v10, v0
	v_mov_b32_e32 v11, v0
	v_mov_b32_e32 v12, v0
	v_mov_b32_e32 v13, v0
	v_mov_b32_e32 v14, v0
	v_mov_b32_e32 v15, v0
	v_mov_b32_e32 v16, v0
	v_mov_b32_e32 v17, v0
	v_mov_b32_e32 v18, v0
	v_mov_b32_e32 v19, v0
	v_mov_b32_e32 v20, v0
	v_mov_b32_e32 v21, v0
	v_mov_b32_e32 v22, v0
	v_mov_b32_e32 v23, v0
	v_mov_b32_e32 v24, v0
	v_mov_b32_e32 v25, v0
	v_mov_b32_e32 v26, v0
	v_mov_b32_e32 v27, v0
	v_mov_b32_e32 v28, v0
	v_mov_b32_e32 v29, v0
	v_mov_b32_e32 v30, v0
	v_mov_b32_e32 v31, v0
; #define MFMA32(a, b, c) __builtin_amdgcn_mfma_f32_32x32x16_bf16((a), (b), (c), 0, 0, 0)
; template <class Epi>
; DI void gemm128(const bf16_t* __restrict__ A, int lda, const bf16_t* __restrict__ B, int ldb, int K, int m0, int n0,
;                 bf16_t* sA, bf16_t* sB, Epi epi) {
;     ...
;   for (int kt = 0; kt < nk; ++kt) {
;     __syncthreads();
;     *(u32x4*)(sA + (lr) * LDS_ROW + lc) = ra0; *(u32x4*)(sA + (lr + 32) * LDS_ROW + lc) = ra1;
;     *(u32x4*)(sA + (lr + 64) * LDS_ROW + lc) = ra2; *(u32x4*)(sA + (lr + 96) * LDS_ROW + lc) = ra3;
;     *(u32x4*)(sB + (lr) * LDS_ROW + lc) = rb0; *(u32x4*)(sB + (lr + 32) * LDS_ROW + lc) = rb1;
;     *(u32x4*)(sB + (lr + 64) * LDS_ROW + lc) = rb2; *(u32x4*)(sB + (lr + 96) * LDS_ROW + lc) = rb3;
;     __syncthreads();
;     if (kt + 1 < nk) {
;       const int ko2 = (kt + 1) * 64;
;       ra0 = *(const u32x4*)(Ap + ko2); ra1 = *(const u32x4*)(Ap + (size_t)32 * lda + ko2);
;       ra2 = *(const u32x4*)(Ap + (size_t)64 * lda + ko2); ra3 = *(const u32x4*)(Ap + (size_t)96 * lda + ko2);
;       rb0 = *(const u32x4*)(Bp + ko2); rb1 = *(const u32x4*)(Bp + (size_t)32 * ldb + ko2);
;       rb2 = *(const u32x4*)(Bp + (size_t)64 * ldb + ko2); rb3 = *(const u32x4*)(Bp + (size_t)96 * ldb + ko2);
;     }
; #pragma unroll
;     for (int s = 0; s < 4; ++s) {
;       const int ko = s * 16 + (lane >> 5) * 8;
;       bf16x8 a0 = *(const bf16x8*)(sA + (wm * 64 + (lane & 31)) * LDS_ROW + ko);
;       bf16x8 a1 = *(const bf16x8*)(sA + (wm * 64 + 32 + (lane & 31)) * LDS_ROW + ko);
;       bf16x8 b0 = *(const bf16x8*)(sB + (wn * 64 + (lane & 31)) * LDS_ROW + ko);
;       bf16x8 b1 = *(const bf16x8*)(sB + (wn * 64 + 32 + (lane & 31)) * LDS_ROW + ko);
;       acc[0][0] = MFMA32(a0, b0, acc[0][0]);
;       acc[0][1] = MFMA32(a0, b1, acc[0][1]);
;       acc[1][0] = MFMA32(a1, b0, acc[1][0]);
;       acc[1][1] = MFMA32(a1, b1, acc[1][1]);
;     }
;   }
; #pragma unroll
;   for (int i = 0; i < 2; ++i)
; #pragma unroll
;     for (int j = 0; j < 2; ++j)
; #pragma unroll
;       for (int r = 0; r < 16; ++r) {
;         const int m = m0 + wm * 64 + i * 32 + crow32(r, lane >> 5);
;         const int n = n0 + wn * 64 + j * 32 + (lane & 31);
;         epi(m, n, acc[i][j][r]);
;       }
; __global__ void __launch_bounds__(256, 2) hymba_mega(Params p) {
;     ...
;                 [&](int m, int n, float v) { if (n < 4112) G[(size_t)(n - 4096) * T_TOK + m] = v; });
.LBB0_223:
	s_barrier
	s_waitcnt vmcnt(7)
	ds_write_b128 v66, v[200:203]
	s_waitcnt vmcnt(6)
	ds_write_b128 v66, v[204:207] offset:4608
	s_waitcnt vmcnt(5)
	ds_write_b128 v66, v[208:211] offset:9216
	s_waitcnt vmcnt(4)
	ds_write_b128 v66, v[212:215] offset:13824
	s_waitcnt vmcnt(3)
	ds_write_b128 v66, v[216:219] offset:18432
	s_waitcnt vmcnt(2)
	ds_write_b128 v66, v[220:223] offset:23040
	s_waitcnt vmcnt(1)
	ds_write_b128 v66, v[224:227] offset:27648
	s_waitcnt vmcnt(0)
	ds_write_b128 v66, v[232:235] offset:32256
	s_waitcnt lgkmcnt(0)
	s_barrier
	v_lshl_add_u64 v[252:253], v[68:69], 0, s[10:11]
	v_lshl_add_u64 v[254:255], v[70:71], 0, s[10:11]
	ds_read_b128 v[32:35], v64
	ds_read_b128 v[36:39], v65 offset:18432
	ds_read_b128 v[40:43], v64 offset:32
	ds_read_b128 v[44:47], v65 offset:18464
	s_waitcnt lgkmcnt(2)
	v_mfma_f32_32x32x16_bf16 v[16:31], v[32:35], v[36:39], v[16:31]
	v_add_co_u32_e64 v198, s[98:99], s4, v252
	s_nop 0
	ds_read_b128 v[32:35], v64 offset:4608
	ds_read_b128 v[48:51], v64 offset:4640
	ds_read_b128 v[52:55], v64 offset:4672
	ds_read_b128 v[56:59], v64 offset:64
	ds_read_b128 v[60:63], v64 offset:96
	s_add_u32 s10, s10, 0x80
	s_addc_u32 s11, s11, 0
	s_cmpk_eq_i32 s10, 0x780
	s_waitcnt lgkmcnt(4)
	v_mfma_f32_32x32x16_bf16 v[0:15], v[32:35], v[36:39], v[0:15]
	v_addc_co_u32_e64 v199, s[98:99], 0, v253, s[98:99]
	global_load_dwordx4 v[200:203], v[252:253], off offset:128
	global_load_dwordx4 v[204:207], v[198:199], off offset:128
	ds_read_b128 v[74:77], v64 offset:4704
	ds_read_b128 v[32:35], v65 offset:18496
	ds_read_b128 v[78:81], v65 offset:18528
	v_mfma_f32_32x32x16_bf16 v[16:31], v[40:43], v[44:47], v[16:31]
	v_add_co_u32_e64 v228, vcc, s5, v252
	v_add_co_u32_e64 v198, s[98:99], s12, v252
	s_waitcnt lgkmcnt(6)
	v_mfma_f32_32x32x16_bf16 v[0:15], v[48:51], v[44:47], v[0:15]
	v_addc_co_u32_e64 v229, vcc, 0, v253, vcc
	v_addc_co_u32_e64 v199, s[98:99], 0, v253, s[98:99]
	global_load_dwordx4 v[208:211], v[228:229], off offset:128
	global_load_dwordx4 v[212:215], v[198:199], off offset:128
	s_waitcnt lgkmcnt(1)
	v_mfma_f32_32x32x16_bf16 v[16:31], v[56:59], v[32:35], v[16:31]
	v_add_co_u32_e64 v228, vcc, s20, v254
	v_add_co_u32_e64 v198, s[98:99], s21, v254
	v_mfma_f32_32x32x16_bf16 v[0:15], v[52:55], v[32:35], v[0:15]
	v_addc_co_u32_e64 v229, vcc, 0, v255, vcc
	v_addc_co_u32_e64 v199, s[98:99], 0, v255, s[98:99]
	global_load_dwordx4 v[216:219], v[228:229], off offset:128
	global_load_dwordx4 v[220:223], v[198:199], off offset:128
	s_waitcnt lgkmcnt(0)
	v_mfma_f32_32x32x16_bf16 v[16:31], v[60:63], v[78:81], v[16:31]
	v_add_co_u32_e64 v228, vcc, s28, v254
	v_add_co_u32_e64 v198, s[98:99], s29, v254
	v_mfma_f32_32x32x16_bf16 v[0:15], v[74:77], v[78:81], v[0:15]
	v_addc_co_u32_e64 v229, vcc, 0, v255, vcc
	v_addc_co_u32_e64 v199, s[98:99], 0, v255, s[98:99]
	global_load_dwordx4 v[224:227], v[228:229], off offset:128
	global_load_dwordx4 v[232:235], v[198:199], off offset:128
	s_cbranch_scc0 .LBB0_223
	s_barrier
	s_waitcnt vmcnt(7)
	ds_write_b128 v66, v[200:203]
	s_waitcnt vmcnt(6)
	ds_write_b128 v66, v[204:207] offset:4608
	s_waitcnt vmcnt(5)
	ds_write_b128 v66, v[208:211] offset:9216
	s_waitcnt vmcnt(4)
	ds_write_b128 v66, v[212:215] offset:13824
	s_waitcnt vmcnt(3)
	ds_write_b128 v66, v[216:219] offset:18432
	s_waitcnt vmcnt(2)
	ds_write_b128 v66, v[220:223] offset:23040
	s_waitcnt vmcnt(1)
	ds_write_b128 v66, v[224:227] offset:27648
	s_waitcnt vmcnt(0)
	ds_write_b128 v66, v[232:235] offset:32256
	s_waitcnt lgkmcnt(0)
	s_barrier
	ds_read_b128 v[32:35], v64
	ds_read_b128 v[36:39], v65 offset:18432
	ds_read_b128 v[40:43], v64 offset:32
	ds_read_b128 v[44:47], v65 offset:18464
	s_waitcnt lgkmcnt(2)
	v_mfma_f32_32x32x16_bf16 v[16:31], v[32:35], v[36:39], v[16:31]
	ds_read_b128 v[32:35], v64 offset:4608
	ds_read_b128 v[48:51], v64 offset:4640
	s_waitcnt lgkmcnt(1)
	v_mfma_f32_32x32x16_bf16 v[0:15], v[32:35], v[36:39], v[0:15]
	v_mfma_f32_32x32x16_bf16 v[16:31], v[40:43], v[44:47], v[16:31]
	s_waitcnt lgkmcnt(0)
	v_mfma_f32_32x32x16_bf16 v[0:15], v[48:51], v[44:47], v[0:15]
	ds_read_b128 v[32:35], v64 offset:64
	ds_read_b128 v[36:39], v65 offset:18496
	ds_read_b128 v[40:43], v64 offset:96
	ds_read_b128 v[44:47], v65 offset:18528
	s_waitcnt lgkmcnt(2)
	v_mfma_f32_32x32x16_bf16 v[16:31], v[32:35], v[36:39], v[16:31]
	ds_read_b128 v[32:35], v64 offset:4672
	ds_read_b128 v[48:51], v64 offset:4704
	s_waitcnt lgkmcnt(1)
	v_mfma_f32_32x32x16_bf16 v[0:15], v[32:35], v[36:39], v[0:15]
	v_or_b32_e32 v32, 0x1000, v73
	v_cmp_gt_u32_e32 vcc, s34, v32
	v_mfma_f32_32x32x16_bf16 v[16:31], v[40:43], v[44:47], v[16:31]
	s_waitcnt lgkmcnt(0)
	v_mfma_f32_32x32x16_bf16 v[0:15], v[48:51], v[44:47], v[0:15]
	s_and_saveexec_b64 s[10:11], vcc
	s_cbranch_execz .LBB0_226
	v_add_u32_e32 v33, s64, v67
	v_lshrrev_b32_e32 v34, 3, v72
	v_and_or_b32 v34, v34, 4, v33
	v_lshlrev_b32_e32 v176, 16, v32
	v_ashrrev_i32_e32 v35, 31, v34
	v_lshl_add_u64 v[32:33], s[30:31], 0, v[176:177]
	v_lshl_add_u64 v[32:33], v[34:35], 2, v[32:33]
	v_add_co_u32_e32 v34, vcc, 0xf0000000, v32
	s_nop 1
	v_addc_co_u32_e32 v35, vcc, -1, v33, vcc
	global_store_dwordx4 v[34:35], v[16:19], off
	s_nop 1
	v_add_co_u32_e32 v16, vcc, 0xf0001000, v32
	s_nop 1
	v_addc_co_u32_e32 v17, vcc, -1, v33, vcc
	global_store_dwordx4 v[16:17], v[20:23], off offset:-4064
	global_store_dwordx4 v[16:17], v[24:27], off offset:-4032
	global_store_dwordx4 v[16:17], v[28:31], off offset:-4000
	global_store_dwordx4 v[16:17], v[0:3], off offset:-3968
	global_store_dwordx4 v[16:17], v[4:7], off offset:-3936
	global_store_dwordx4 v[16:17], v[8:11], off offset:-3904
	global_store_dwordx4 v[16:17], v[12:15], off offset:-3872
